# panel hand-off polls of P8 / P9 / P12: ring of four polls in flight, success path no longer drains the outstanding polls
# speedup vs baseline: 1.0111x; 1.0006x over previous
; __device__ __forceinline__ unsigned xb_ld(unsigned* p)              { return __hip_atomic_load(p, __ATOMIC_RELAXED, __HIP_MEMORY_SCOPE_AGENT); }
; __device__ __forceinline__ unsigned xb_add(unsigned* p, unsigned v) { return __hip_atomic_fetch_add(p, v, __ATOMIC_RELAXED, __HIP_MEMORY_SCOPE_AGENT); }
; #define XB_SPIN(cond, bar) do { unsigned _sp = 0; while (cond) { __builtin_amdgcn_s_sleep(1); \
;     if ((++_sp & 255u) == 0u) { if (xb_ld(&(bar)[XB_TMO])) break; if (_sp > XB_SPIN_CAP) { atomicAdd(&(bar)[XB_TMO], 1u); break; } } } } while (0)
; __global__ void __launch_bounds__(NTHR, 2) k_main(Args a) {
;     ...
;         for (int i = 0; S.next(i, u); ++i) {
;             __syncthreads();
;             if (tid == 0) { unsigned* cw = &((unsigned*)ws)[12288 + 16 * u.pm]; XB_SPIN(xb_ld(cw) < (unsigned)(D / 256), (unsigned*)ws);
;                 __builtin_amdgcn_fence(__ATOMIC_ACQUIRE, "agent"); asm volatile("s_waitcnt vmcnt(0)" ::: "memory"); }
;             __syncthreads();
;             const int r0 = u.pm * 256 + u.pn * 64;
;             xn2_rows(HB, a.norm_ffn_g, XNB, XQ, XS, r0 + wave, 8, lane, r0 + 64);
;             asm volatile("s_waitcnt vmcnt(0)" ::: "memory");
;             __syncthreads();
;             if (tid == 0) (void)xb_add(&((unsigned*)ws)[6144 + 16 * u.pm], 1u);
;         }
.Lp8_ring_ok:
	s_nop 0
	s_branch .LBB0_564

; __device__ __forceinline__ unsigned xb_ld(unsigned* p)              { return __hip_atomic_load(p, __ATOMIC_RELAXED, __HIP_MEMORY_SCOPE_AGENT); }
; #define XB_SPIN(cond, bar) do { unsigned _sp = 0; while (cond) { __builtin_amdgcn_s_sleep(1); \
;     if ((++_sp & 255u) == 0u) { if (xb_ld(&(bar)[XB_TMO])) break; if (_sp > XB_SPIN_CAP) { atomicAdd(&(bar)[XB_TMO], 1u); break; } } } } while (0)
; __global__ void __launch_bounds__(NTHR, 2) k_main(Args a) {
;     ...
;           if (tid == 0) { pg8::Unit u; for (int i = 0; S.next(i, u); ++i) { unsigned* cw = &((unsigned*)ws)[6144 + 16 * u.pm]; XB_SPIN(xb_ld(cw) < 4u, (unsigned*)ws); }
;               XB_SPIN(xb_ld(&((unsigned*)ws)[14336]) < 256u, (unsigned*)ws);
;               __builtin_amdgcn_fence(__ATOMIC_ACQUIRE, "agent"); asm volatile("s_waitcnt vmcnt(0)" ::: "memory"); }
.LBB0_597:
	s_movk_i32 s3, 0xff
	s_add_u32 s6, s90, 0xe000
	s_addc_u32 s7, s91, 0
	s_waitcnt vmcnt(4)
	v_mov_b32_e32 v1, v8
	v_cmp_lt_u32_e32 vcc, s3, v1
	s_cbranch_vccnz .LBB0_610
	s_mov_b32 s14, 1
	v_mov_b32_e32 v1, 0
	s_branch .LBB0_600

; __device__ __forceinline__ unsigned xb_ld(unsigned* p)              { return __hip_atomic_load(p, __ATOMIC_RELAXED, __HIP_MEMORY_SCOPE_AGENT); }
; #define XB_SPIN(cond, bar) do { unsigned _sp = 0; while (cond) { __builtin_amdgcn_s_sleep(1); \
;     if ((++_sp & 255u) == 0u) { if (xb_ld(&(bar)[XB_TMO])) break; if (_sp > XB_SPIN_CAP) { atomicAdd(&(bar)[XB_TMO], 1u); break; } } } } while (0)
; __global__ void __launch_bounds__(NTHR, 2) k_main(Args a) {
;     ...
;               XB_SPIN(xb_ld(&((unsigned*)ws)[14336]) < 256u, (unsigned*)ws);
;               __builtin_amdgcn_fence(__ATOMIC_ACQUIRE, "agent"); asm volatile("s_waitcnt vmcnt(0)" ::: "memory"); }
.LBB0_610:
	s_nop 0
	s_nop 0
